# RWKV scan identity-row waves: rank-1 state update with the two-block v_mfma_f32_32x32x1_2b_f32 (half the MFMA time of the K=2 form with a zero half)
# speedup vs baseline: 1.0412x; 1.0088x over previous
; __device__ __forceinline__ int tidx() { int t = threadIdx.x; asm volatile("" : "+v"(t)); return t; }
; __device__ __forceinline__ int bidx() { int b = blockIdx.x; asm volatile("" : "+s"(b)); return b; }
; __device__ __forceinline__ float bf2f(unsigned short b) { return __uint_as_float((unsigned)b << 16); }
; __device__ __forceinline__ f2 pfma(f2 a, f2 b, f2 c) { return __builtin_elementwise_fma(a, b, c); }
; template <bool ID> __device__ __forceinline__ void rwkv_scan(const bf16_t* __restrict__ R, const bf16_t* __restrict__ EW, const bf16_t* __restrict__ K, const bf16_t* __restrict__ V, ...
;     unsigned short q1[6], q2[6];
;     { unsigned o = base; q1[0] = R[o]; q1[1] = EW[o]; q1[2] = K[o]; q1[3] = V[o]; q1[4] = A[o]; q1[5] = B[o];
;       o = base + 512u; q2[0] = R[o]; q2[1] = EW[o]; q2[2] = K[o]; q2[3] = V[o]; q2[4] = A[o]; q2[5] = B[o]; }
;     const LAS f32x4* pa = (const LAS f32x4*)L;
;     float sav, sai;
;     { L[lane] = bf2f(q1[4]);
;       f2 av = {0.f, 0.f}, ai = {0.f, 0.f};
; #pragma unroll
;       for (int q = 0; q < 16; ++q) { const f32x4 a4 = pa[q]; const f2 a01 = {a4[0], a4[1]}, a23 = {a4[2], a4[3]};
;           av = pfma(Sv[2 * q], a01, av); av = pfma(Sv[2 * q + 1], a23, av); if (ID) { ai = pfma(Si[2 * q], a01, ai); ai = pfma(Si[2 * q + 1], a23, ai); } }
;       sav = av[0] + av[1]; sai = ai[0] + ai[1]; }
; __device__ void phase_rwkv_scan(const Ctx& p, int l, LAS unsigned char* lds) {
;     ...
;         for (int item = bidx() * 4 + wave; item < 1024; item += gridDim.x * 4) {
;             const int b = item >> 9, c = (item >> 3) & 63, h = item & 7;
;             f2 Sv[32], Si[32]; const int li = tidx() & 63;
; #pragma unroll
;             for (int i = 0; i < 32; ++i) { Sv[i] = (f2){0.f, 0.f}; Si[i] = (f2){(2 * i == li) ? 1.f : 0.f, (2 * i + 1 == li) ? 1.f : 0.f}; }
;             rwkv_scan<true>(R, EW, K, V, A, B, (unsigned)((b * 8192 + c * 128) * 512 + h * 64 + lane), 128, Sv, Si, YH, QH, L, lane);
.Lscan_i:
	v_lshrrev_b32_e32 v78, 5, v139
	v_and_b32_e32 v79, 31, v139
	s_mov_b32 s26, -1
	s_mov_b32 s27, 0
	s_lshl_b32 s14, s36, 13
	s_and_b32 s14, s14, 0xffff0000
	s_lshl_b32 s15, s36, 6
	s_and_b32 s15, s15, 0x1c0
	s_or_b32 s14, s14, s15
	v_add_lshl_u32 v72, s14, v139, 1
	v_add_lshl_u32 v81, s14, v79, 1
	v_mov_b32_e32 v74, s20
	v_mov_b32_e32 v75, s21
	v_add_co_u32_e32 v74, vcc, v74, v81
	s_nop 1
	v_addc_co_u32_e32 v75, vcc, 0, v75, vcc
	v_lshl_add_u32 v76, v78, 4, s10
	v_lshl_add_u32 v77, v139, 2, s10
	v_lshl_add_u32 v251, v79, 2, s10
	v_mov_b32_e32 v246, 1.0
	v_lshlrev_b32_e32 v81, 2, v78
	v_sub_u32_e32 v81, v79, v81
	global_load_ushort v244, v72, s[12:13]
	global_load_ushort v224, v72, s[4:5] offset:0
	global_load_ushort v225, v72, s[0:1] offset:0
	global_load_ushort v226, v72, s[12:13] offset:1024
	global_load_ushort v227, v[74:75], off offset:0
	global_load_ushort v228, v[74:75], off offset:64
	global_load_ushort v230, v72, s[4:5] offset:1024
	global_load_ushort v231, v72, s[0:1] offset:1024
	global_load_ushort v232, v72, s[12:13] offset:2048
	global_load_ushort v233, v[74:75], off offset:1024
	global_load_ushort v234, v[74:75], off offset:1088
	global_load_ushort v82, v72, s[4:5] offset:2048
	global_load_ushort v83, v72, s[0:1] offset:2048
	global_load_ushort v84, v72, s[12:13] offset:3072
	global_load_ushort v85, v[74:75], off offset:2048
	global_load_ushort v86, v[74:75], off offset:2112
	v_add_u32_e32 v72, 0xc00, v72
	v_lshl_add_u64 v[74:75], v[74:75], 0, s[54:55]
	v_lshl_add_u64 v[74:75], v[74:75], 0, s[54:55]
	v_lshl_add_u64 v[74:75], v[74:75], 0, s[54:55]
	global_load_ushort v88, v72, s[4:5] offset:0
	global_load_ushort v89, v72, s[0:1] offset:0
	global_load_ushort v90, v72, s[12:13] offset:1024
	global_load_ushort v91, v[74:75], off offset:0
	global_load_ushort v92, v[74:75], off offset:64
	v_add_u32_e32 v72, 0x400, v72
	v_lshl_add_u64 v[74:75], v[74:75], 0, s[54:55]
	v_mov_b32_e32 v32, 0
	v_mov_b32_e32 v33, 0
	v_mov_b32_e32 v34, 0
	v_mov_b32_e32 v35, 0
	v_mov_b32_e32 v36, 0
	v_mov_b32_e32 v37, 0
	v_mov_b32_e32 v38, 0
	v_mov_b32_e32 v39, 0
	v_mov_b32_e32 v40, 0
	v_mov_b32_e32 v41, 0
	v_mov_b32_e32 v42, 0
	v_mov_b32_e32 v43, 0
	v_mov_b32_e32 v44, 0
	v_mov_b32_e32 v45, 0
	v_mov_b32_e32 v46, 0
	v_mov_b32_e32 v47, 0
	v_mov_b32_e32 v16, 0
	v_mov_b32_e32 v17, 0
	v_mov_b32_e32 v18, 0
	v_mov_b32_e32 v19, 0
	v_mov_b32_e32 v20, 0
	v_mov_b32_e32 v21, 0
	v_mov_b32_e32 v22, 0
	v_mov_b32_e32 v23, 0
	v_mov_b32_e32 v24, 0
	v_mov_b32_e32 v25, 0
	v_mov_b32_e32 v26, 0
	v_mov_b32_e32 v27, 0
	v_mov_b32_e32 v28, 0
	v_mov_b32_e32 v29, 0
	v_mov_b32_e32 v30, 0
	v_mov_b32_e32 v31, 0
	v_cmp_eq_u32_e64 s[14:15], 0, v81
	s_nop 1
	v_cndmask_b32_e64 v0, 0, 1.0, s[14:15]
	v_cndmask_b32_e64 v48, 0, 1.0, s[14:15]
	v_cmp_eq_u32_e64 s[14:15], 1, v81
	s_nop 1
	v_cndmask_b32_e64 v1, 0, 1.0, s[14:15]
	v_cndmask_b32_e64 v49, 0, 1.0, s[14:15]
	v_cmp_eq_u32_e64 s[14:15], 2, v81
	s_nop 1
	v_cndmask_b32_e64 v2, 0, 1.0, s[14:15]
	v_cndmask_b32_e64 v50, 0, 1.0, s[14:15]
	v_cmp_eq_u32_e64 s[14:15], 3, v81
	s_nop 1
	v_cndmask_b32_e64 v3, 0, 1.0, s[14:15]
	v_cndmask_b32_e64 v51, 0, 1.0, s[14:15]
	v_cmp_eq_u32_e64 s[14:15], 8, v81
	s_nop 1
	v_cndmask_b32_e64 v4, 0, 1.0, s[14:15]
	v_cndmask_b32_e64 v52, 0, 1.0, s[14:15]
	v_cmp_eq_u32_e64 s[14:15], 9, v81
	s_nop 1
	v_cndmask_b32_e64 v5, 0, 1.0, s[14:15]
	v_cndmask_b32_e64 v53, 0, 1.0, s[14:15]
	v_cmp_eq_u32_e64 s[14:15], 10, v81
	s_nop 1
	v_cndmask_b32_e64 v6, 0, 1.0, s[14:15]
	v_cndmask_b32_e64 v54, 0, 1.0, s[14:15]
	v_cmp_eq_u32_e64 s[14:15], 11, v81
	s_nop 1
	v_cndmask_b32_e64 v7, 0, 1.0, s[14:15]
	v_cndmask_b32_e64 v55, 0, 1.0, s[14:15]
	v_cmp_eq_u32_e64 s[14:15], 16, v81
	s_nop 1
	v_cndmask_b32_e64 v8, 0, 1.0, s[14:15]
	v_cndmask_b32_e64 v56, 0, 1.0, s[14:15]
	v_cmp_eq_u32_e64 s[14:15], 17, v81
	s_nop 1
	v_cndmask_b32_e64 v9, 0, 1.0, s[14:15]
	v_cndmask_b32_e64 v57, 0, 1.0, s[14:15]
	v_cmp_eq_u32_e64 s[14:15], 18, v81
	s_nop 1
	v_cndmask_b32_e64 v10, 0, 1.0, s[14:15]
	v_cndmask_b32_e64 v58, 0, 1.0, s[14:15]
	v_cmp_eq_u32_e64 s[14:15], 19, v81
	s_nop 1
	v_cndmask_b32_e64 v11, 0, 1.0, s[14:15]
	v_cndmask_b32_e64 v59, 0, 1.0, s[14:15]
	v_cmp_eq_u32_e64 s[14:15], 24, v81
	s_nop 1
	v_cndmask_b32_e64 v12, 0, 1.0, s[14:15]
	v_cndmask_b32_e64 v60, 0, 1.0, s[14:15]
	v_cmp_eq_u32_e64 s[14:15], 25, v81
	s_nop 1
	v_cndmask_b32_e64 v13, 0, 1.0, s[14:15]
	v_cndmask_b32_e64 v61, 0, 1.0, s[14:15]
	v_cmp_eq_u32_e64 s[14:15], 26, v81
	s_nop 1
	v_cndmask_b32_e64 v14, 0, 1.0, s[14:15]
	v_cndmask_b32_e64 v62, 0, 1.0, s[14:15]
	v_cmp_eq_u32_e64 s[14:15], 27, v81
	s_nop 1
	v_cndmask_b32_e64 v15, 0, 1.0, s[14:15]
	v_cndmask_b32_e64 v63, 0, 1.0, s[14:15]
	s_waitcnt vmcnt(15)
	v_lshlrev_b32_e32 v78, 16, v224
	v_mul_f32_e32 v78, 0xbfb8aa3b, v78
	v_exp_f32_e32 v78, v78
	v_lshlrev_b32_e32 v79, 16, v225
	v_lshlrev_b32_e32 v80, 16, v226
	v_mul_f32_e32 v246, v246, v78
	v_mul_f32_e32 v79, v79, v246
	v_mul_f32_e32 v80, v80, v246
	v_rcp_f32_e32 v248, v246
	s_nop 0
	ds_write2st64_b32 v77, v248, v79 offset0:0 offset1:1
	ds_write_b32 v77, v80 offset:512
	ds_read_b32 v249, v251 offset:0
	ds_read_b32 v250, v251 offset:128
	v_lshlrev_b32_e32 v240, 16, v227
	v_lshlrev_b32_e32 v241, 16, v228
	s_waitcnt lgkmcnt(0)
	v_mul_f32_e32 v240, v240, v249
	v_mul_f32_e32 v241, v241, v250
	v_lshlrev_b32_e32 v244, 16, v244
	s_movk_i32 s41, 0
; template <bool ID> __device__ __forceinline__ void rwkv_scan(const bf16_t* __restrict__ R, const bf16_t* __restrict__ EW, const bf16_t* __restrict__ K, const bf16_t* __restrict__ V, ...
;     ...
;         L[lane] = bf2f(q2[4]); L[64 + lane] = __expf(-bf2f(q1[1])); L[128 + lane] = bf2f(q1[5]); L[192 + lane] = bf2f(q1[2]); L[256 + lane] = bf2f(q1[0]);
;         const float v = bf2f(q1[3]);
; #pragma unroll
;         for (int j = 0; j < 6; ++j) q1[j] = q2[j];
;         { const unsigned o = base + (unsigned)(s + 2 < nsteps ? s + 2 : nsteps - 1) * 512u; q2[0] = R[o]; q2[1] = EW[o]; q2[2] = K[o]; q2[3] = V[o]; q2[4] = A[o]; q2[5] = B[o]; }
;         const f2 sav2 = {sav, sav}, sai2 = {sai, sai}, v2 = {v, v};
;         f2 yv = {0.f, 0.f}, yi = {0.f, 0.f}, yv1 = {0.f, 0.f}, yi1 = {0.f, 0.f}, nv = {0.f, 0.f}, ni = {0.f, 0.f}, nv1 = {0.f, 0.f}, ni1 = {0.f, 0.f};
;         f32x4 ca = pa[0], cw = pa[16], cb = pa[32], ck = pa[48], cr = pa[64];
; #pragma unroll
;         for (int q = 0; q < 16; ++q) {
;             const f32x4 a4 = ca, w4 = cw, b4 = cb, k4 = ck, r4 = cr;
;             if (q < 15) { ca = pa[1 + q]; cw = pa[17 + q]; cb = pa[33 + q]; ck = pa[49 + q]; cr = pa[65 + q]; }
;             __builtin_amdgcn_sched_barrier(0);
;             { const f2 a2 = {a4[0], a4[1]}, w2 = {w4[0], w4[1]}, b2 = {b4[0], b4[1]}, k2 = {k4[0], k4[1]}, r2 = {r4[0], r4[1]};
;               f2 tv = sav2 * b2; tv = pfma(v2, k2, tv); Sv[2 * q] = pfma(Sv[2 * q], w2, tv); yv = pfma(Sv[2 * q], r2, yv); nv = pfma(Sv[2 * q], a2, nv);
;               if (ID) { const f2 ti = sai2 * b2; Si[2 * q] = pfma(Si[2 * q], w2, ti); yi = pfma(Si[2 * q], r2, yi); ni = pfma(Si[2 * q], a2, ni); } }
;             { const f2 a2 = {a4[2], a4[3]}, w2 = {w4[2], w4[3]}, b2 = {b4[2], b4[3]}, k2 = {k4[2], k4[3]}, r2 = {r4[2], r4[3]};
;               f2 tv = sav2 * b2; tv = pfma(v2, k2, tv); Sv[2 * q + 1] = pfma(Sv[2 * q + 1], w2, tv); yv1 = pfma(Sv[2 * q + 1], r2, yv1); nv1 = pfma(Sv[2 * q + 1], a2, nv1);
;               if (ID) { const f2 ti = sai2 * b2; Si[2 * q + 1] = pfma(Si[2 * q + 1], w2, ti); yi1 = pfma(Si[2 * q + 1], r2, yi1); ni1 = pfma(Si[2 * q + 1], a2, ni1); } }
;         }
;         sav = (nv[0] + nv[1]) + (nv1[0] + nv1[1]); sai = (ni[0] + ni[1]) + (ni1[0] + ni1[1]);
;         const unsigned cbo = base + (unsigned)s * 512u;
.Lscan_i_loop:
	ds_read_b128 v[192:195], v76 offset:256
	ds_read_b128 v[196:199], v76 offset:288
	ds_read_b128 v[200:203], v76 offset:320
	ds_read_b128 v[204:207], v76 offset:352
	ds_read_b128 v[208:211], v76 offset:512
	ds_read_b128 v[212:215], v76 offset:544
	ds_read_b128 v[216:219], v76 offset:576
	ds_read_b128 v[220:223], v76 offset:608
	global_load_ushort v224, v72, s[4:5] offset:0
	global_load_ushort v225, v72, s[0:1] offset:0
	global_load_ushort v226, v72, s[12:13] offset:1024
	global_load_ushort v227, v[74:75], off offset:0
	global_load_ushort v228, v[74:75], off offset:64
	v_mfma_f32_32x32x1_2b_f32 v[0:31], v240, v244, v[0:31]
	ds_read_b128 v[148:151], v76 offset:384
	ds_read_b128 v[152:155], v76 offset:416
	ds_read_b128 v[156:159], v76 offset:448
	ds_read_b128 v[160:163], v76 offset:480
	ds_read_b128 v[164:167], v76 offset:640
	ds_read_b128 v[168:171], v76 offset:672
	ds_read_b128 v[172:175], v76 offset:704
	ds_read_b128 v[176:179], v76 offset:736
	v_mfma_f32_32x32x1_2b_f32 v[32:63], v241, v244, v[32:63]
	s_waitcnt vmcnt(15)
	v_lshlrev_b32_e32 v78, 16, v230
	v_mul_f32_e32 v78, 0xbfb8aa3b, v78
	v_exp_f32_e32 v78, v78
	v_lshlrev_b32_e32 v79, 16, v231
	v_lshlrev_b32_e32 v80, 16, v232
	v_mul_f32_e32 v246, v246, v78
	v_mul_f32_e32 v79, v79, v246
	v_mul_f32_e32 v80, v80, v246
	v_rcp_f32_e32 v248, v246
	s_nop 0
	ds_write2st64_b32 v77, v248, v79 offset0:3 offset1:4
	ds_write_b32 v77, v80 offset:1280
	s_waitcnt lgkmcnt(10)
	v_pk_mul_f32 v[64:65], v[0:1], v[192:193]
	v_pk_mul_f32 v[68:69], v[0:1], v[208:209]
	v_pk_fma_f32 v[64:65], v[2:3], v[194:195], v[64:65]
	v_pk_fma_f32 v[68:69], v[2:3], v[210:211], v[68:69]
	v_pk_fma_f32 v[64:65], v[4:5], v[196:197], v[64:65]
	v_pk_fma_f32 v[68:69], v[4:5], v[212:213], v[68:69]
	v_pk_fma_f32 v[64:65], v[6:7], v[198:199], v[64:65]
	v_pk_fma_f32 v[68:69], v[6:7], v[214:215], v[68:69]
	v_pk_fma_f32 v[64:65], v[8:9], v[200:201], v[64:65]
	v_pk_fma_f32 v[68:69], v[8:9], v[216:217], v[68:69]
	v_pk_fma_f32 v[64:65], v[10:11], v[202:203], v[64:65]
	v_pk_fma_f32 v[68:69], v[10:11], v[218:219], v[68:69]
	v_pk_fma_f32 v[64:65], v[12:13], v[204:205], v[64:65]
	v_pk_fma_f32 v[68:69], v[12:13], v[220:221], v[68:69]
	v_pk_fma_f32 v[64:65], v[14:15], v[206:207], v[64:65]
	v_pk_fma_f32 v[68:69], v[14:15], v[222:223], v[68:69]
	v_pk_mul_f32 v[66:67], v[16:17], v[192:193]
	v_pk_mul_f32 v[70:71], v[16:17], v[208:209]
	v_pk_fma_f32 v[66:67], v[18:19], v[194:195], v[66:67]
	v_pk_fma_f32 v[70:71], v[18:19], v[210:211], v[70:71]
	v_pk_fma_f32 v[66:67], v[20:21], v[196:197], v[66:67]
	v_pk_fma_f32 v[70:71], v[20:21], v[212:213], v[70:71]
	v_pk_fma_f32 v[66:67], v[22:23], v[198:199], v[66:67]
	v_pk_fma_f32 v[70:71], v[22:23], v[214:215], v[70:71]
	v_pk_fma_f32 v[66:67], v[24:25], v[200:201], v[66:67]
	v_pk_fma_f32 v[70:71], v[24:25], v[216:217], v[70:71]
	v_pk_fma_f32 v[66:67], v[26:27], v[202:203], v[66:67]
	v_pk_fma_f32 v[70:71], v[26:27], v[218:219], v[70:71]
	v_pk_fma_f32 v[66:67], v[28:29], v[204:205], v[66:67]
	v_pk_fma_f32 v[70:71], v[28:29], v[220:221], v[70:71]
	v_pk_fma_f32 v[66:67], v[30:31], v[206:207], v[66:67]
	v_pk_fma_f32 v[70:71], v[30:31], v[222:223], v[70:71]
	s_waitcnt lgkmcnt(2)
	v_pk_fma_f32 v[64:65], v[32:33], v[148:149], v[64:65]
	v_pk_fma_f32 v[68:69], v[32:33], v[164:165], v[68:69]
	v_pk_fma_f32 v[64:65], v[34:35], v[150:151], v[64:65]
	v_pk_fma_f32 v[68:69], v[34:35], v[166:167], v[68:69]
	v_pk_fma_f32 v[64:65], v[36:37], v[152:153], v[64:65]
	v_pk_fma_f32 v[68:69], v[36:37], v[168:169], v[68:69]
	v_pk_fma_f32 v[64:65], v[38:39], v[154:155], v[64:65]
	v_pk_fma_f32 v[68:69], v[38:39], v[170:171], v[68:69]
	v_pk_fma_f32 v[64:65], v[40:41], v[156:157], v[64:65]
	v_pk_fma_f32 v[68:69], v[40:41], v[172:173], v[68:69]
	v_pk_fma_f32 v[64:65], v[42:43], v[158:159], v[64:65]
	v_pk_fma_f32 v[68:69], v[42:43], v[174:175], v[68:69]
	v_pk_fma_f32 v[64:65], v[44:45], v[160:161], v[64:65]
	v_pk_fma_f32 v[68:69], v[44:45], v[176:177], v[68:69]
	v_pk_fma_f32 v[64:65], v[46:47], v[162:163], v[64:65]
	v_pk_fma_f32 v[68:69], v[46:47], v[178:179], v[68:69]
	v_pk_fma_f32 v[66:67], v[48:49], v[148:149], v[66:67]
	v_pk_fma_f32 v[70:71], v[48:49], v[164:165], v[70:71]
	v_pk_fma_f32 v[66:67], v[50:51], v[150:151], v[66:67]
	v_pk_fma_f32 v[70:71], v[50:51], v[166:167], v[70:71]
	v_pk_fma_f32 v[66:67], v[52:53], v[152:153], v[66:67]
	v_pk_fma_f32 v[70:71], v[52:53], v[168:169], v[70:71]
	v_pk_fma_f32 v[66:67], v[54:55], v[154:155], v[66:67]
	v_pk_fma_f32 v[70:71], v[54:55], v[170:171], v[70:71]
	v_pk_fma_f32 v[66:67], v[56:57], v[156:157], v[66:67]
	v_pk_fma_f32 v[70:71], v[56:57], v[172:173], v[70:71]
	v_pk_fma_f32 v[66:67], v[58:59], v[158:159], v[66:67]
	v_pk_fma_f32 v[70:71], v[58:59], v[174:175], v[70:71]
	v_pk_fma_f32 v[66:67], v[60:61], v[160:161], v[66:67]
	v_pk_fma_f32 v[70:71], v[60:61], v[176:177], v[70:71]
	v_pk_fma_f32 v[66:67], v[62:63], v[162:163], v[66:67]
	v_pk_fma_f32 v[70:71], v[62:63], v[178:179], v[70:71]
	ds_read_b32 v249, v251 offset:768
	ds_read_b32 v250, v251 offset:896
	v_lshlrev_b32_e32 v240, 16, v233
	v_lshlrev_b32_e32 v241, 16, v234
	s_waitcnt lgkmcnt(0)
; template <bool ID> __device__ __forceinline__ void rwkv_scan(const bf16_t* __restrict__ R, const bf16_t* __restrict__ EW, const bf16_t* __restrict__ K, const bf16_t* __restrict__ V, ...
;     ...
;         L[lane] = bf2f(q2[4]); L[64 + lane] = __expf(-bf2f(q1[1])); L[128 + lane] = bf2f(q1[5]); L[192 + lane] = bf2f(q1[2]); L[256 + lane] = bf2f(q1[0]);
;         const float v = bf2f(q1[3]);
; #pragma unroll
;         for (int j = 0; j < 6; ++j) q1[j] = q2[j];
;         { const unsigned o = base + (unsigned)(s + 2 < nsteps ? s + 2 : nsteps - 1) * 512u; q2[0] = R[o]; q2[1] = EW[o]; q2[2] = K[o]; q2[3] = V[o]; q2[4] = A[o]; q2[5] = B[o]; }
;         const f2 sav2 = {sav, sav}, sai2 = {sai, sai}, v2 = {v, v};
;         f2 yv = {0.f, 0.f}, yi = {0.f, 0.f}, yv1 = {0.f, 0.f}, yi1 = {0.f, 0.f}, nv = {0.f, 0.f}, ni = {0.f, 0.f}, nv1 = {0.f, 0.f}, ni1 = {0.f, 0.f};
;         f32x4 ca = pa[0], cw = pa[16], cb = pa[32], ck = pa[48], cr = pa[64];
; #pragma unroll
;         for (int q = 0; q < 16; ++q) {
;             const f32x4 a4 = ca, w4 = cw, b4 = cb, k4 = ck, r4 = cr;
;             if (q < 15) { ca = pa[1 + q]; cw = pa[17 + q]; cb = pa[33 + q]; ck = pa[49 + q]; cr = pa[65 + q]; }
;             __builtin_amdgcn_sched_barrier(0);
;             { const f2 a2 = {a4[0], a4[1]}, w2 = {w4[0], w4[1]}, b2 = {b4[0], b4[1]}, k2 = {k4[0], k4[1]}, r2 = {r4[0], r4[1]};
;               f2 tv = sav2 * b2; tv = pfma(v2, k2, tv); Sv[2 * q] = pfma(Sv[2 * q], w2, tv); yv = pfma(Sv[2 * q], r2, yv); nv = pfma(Sv[2 * q], a2, nv);
;               if (ID) { const f2 ti = sai2 * b2; Si[2 * q] = pfma(Si[2 * q], w2, ti); yi = pfma(Si[2 * q], r2, yi); ni = pfma(Si[2 * q], a2, ni); } }
;             { const f2 a2 = {a4[2], a4[3]}, w2 = {w4[2], w4[3]}, b2 = {b4[2], b4[3]}, k2 = {k4[2], k4[3]}, r2 = {r4[2], r4[3]};
;               f2 tv = sav2 * b2; tv = pfma(v2, k2, tv); Sv[2 * q + 1] = pfma(Sv[2 * q + 1], w2, tv); yv1 = pfma(Sv[2 * q + 1], r2, yv1); nv1 = pfma(Sv[2 * q + 1], a2, nv1);
;               if (ID) { const f2 ti = sai2 * b2; Si[2 * q + 1] = pfma(Si[2 * q + 1], w2, ti); yi1 = pfma(Si[2 * q + 1], r2, yi1); ni1 = pfma(Si[2 * q + 1], a2, ni1); } }
;         }
;         sav = (nv[0] + nv[1]) + (nv1[0] + nv1[1]); sai = (ni[0] + ni[1]) + (ni1[0] + ni1[1]);
;         const unsigned cbo = base + (unsigned)s * 512u;
	v_mul_f32_e32 v240, v240, v249
	v_mul_f32_e32 v241, v241, v250
	v_add_f32_e32 v68, v68, v69
	v_add_f32_e32 v70, v70, v71
	v_add_f32_e32 v64, v64, v65
	v_add_f32_e32 v66, v66, v67
	v_permlane32_swap_b32_e32 v68, v70
	s_nop 0
	v_permlane32_swap_b32_e32 v64, v66
	v_add_f32_e32 v244, v68, v70
	v_add_f32_e32 v64, v64, v66
	v_bfe_u32 v66, v64, 16, 1
	v_add3_u32 v66, v64, v66, s69
	global_store_short_d16_hi v72, v66, s[24:25] offset:-4096
	v_add_u32_e32 v72, 0x400, v72
	v_lshl_add_u64 v[74:75], v[74:75], 0, s[54:55]
	ds_read_b128 v[148:151], v76 offset:1024
	ds_read_b128 v[152:155], v76 offset:1056
	ds_read_b128 v[156:159], v76 offset:1088
	ds_read_b128 v[160:163], v76 offset:1120
	ds_read_b128 v[164:167], v76 offset:1280
	ds_read_b128 v[168:171], v76 offset:1312
	ds_read_b128 v[172:175], v76 offset:1344
	ds_read_b128 v[176:179], v76 offset:1376
	global_load_ushort v230, v72, s[4:5] offset:0
	global_load_ushort v231, v72, s[0:1] offset:0
	global_load_ushort v232, v72, s[12:13] offset:1024
	global_load_ushort v233, v[74:75], off offset:0
	global_load_ushort v234, v[74:75], off offset:64
	v_mfma_f32_32x32x1_2b_f32 v[0:31], v240, v244, v[0:31]
	ds_read_b128 v[192:195], v76 offset:1152
	ds_read_b128 v[196:199], v76 offset:1184
	ds_read_b128 v[200:203], v76 offset:1216
	ds_read_b128 v[204:207], v76 offset:1248
	ds_read_b128 v[208:211], v76 offset:1408
	ds_read_b128 v[212:215], v76 offset:1440
	ds_read_b128 v[216:219], v76 offset:1472
	ds_read_b128 v[220:223], v76 offset:1504
	v_mfma_f32_32x32x1_2b_f32 v[32:63], v241, v244, v[32:63]
	s_waitcnt vmcnt(16)
	v_lshlrev_b32_e32 v78, 16, v82
	v_mul_f32_e32 v78, 0xbfb8aa3b, v78
	v_exp_f32_e32 v78, v78
	v_lshlrev_b32_e32 v79, 16, v83
	v_lshlrev_b32_e32 v80, 16, v84
	v_mul_f32_e32 v246, v246, v78
	v_mul_f32_e32 v79, v79, v246
	v_mul_f32_e32 v80, v80, v246
	v_rcp_f32_e32 v248, v246
	s_nop 0
	ds_write2st64_b32 v77, v248, v79 offset0:0 offset1:1
	ds_write_b32 v77, v80 offset:512
	s_waitcnt lgkmcnt(10)
	v_pk_mul_f32 v[64:65], v[0:1], v[148:149]
	v_pk_mul_f32 v[68:69], v[0:1], v[164:165]
	v_pk_fma_f32 v[64:65], v[2:3], v[150:151], v[64:65]
	v_pk_fma_f32 v[68:69], v[2:3], v[166:167], v[68:69]
	v_pk_fma_f32 v[64:65], v[4:5], v[152:153], v[64:65]
	v_pk_fma_f32 v[68:69], v[4:5], v[168:169], v[68:69]
	v_pk_fma_f32 v[64:65], v[6:7], v[154:155], v[64:65]
	v_pk_fma_f32 v[68:69], v[6:7], v[170:171], v[68:69]
	v_pk_fma_f32 v[64:65], v[8:9], v[156:157], v[64:65]
	v_pk_fma_f32 v[68:69], v[8:9], v[172:173], v[68:69]
	v_pk_fma_f32 v[64:65], v[10:11], v[158:159], v[64:65]
	v_pk_fma_f32 v[68:69], v[10:11], v[174:175], v[68:69]
	v_pk_fma_f32 v[64:65], v[12:13], v[160:161], v[64:65]
	v_pk_fma_f32 v[68:69], v[12:13], v[176:177], v[68:69]
	v_pk_fma_f32 v[64:65], v[14:15], v[162:163], v[64:65]
	v_pk_fma_f32 v[68:69], v[14:15], v[178:179], v[68:69]
	v_pk_mul_f32 v[66:67], v[16:17], v[148:149]
	v_pk_mul_f32 v[70:71], v[16:17], v[164:165]
	v_pk_fma_f32 v[66:67], v[18:19], v[150:151], v[66:67]
	v_pk_fma_f32 v[70:71], v[18:19], v[166:167], v[70:71]
	v_pk_fma_f32 v[66:67], v[20:21], v[152:153], v[66:67]
	v_pk_fma_f32 v[70:71], v[20:21], v[168:169], v[70:71]
	v_pk_fma_f32 v[66:67], v[22:23], v[154:155], v[66:67]
	v_pk_fma_f32 v[70:71], v[22:23], v[170:171], v[70:71]
	v_pk_fma_f32 v[66:67], v[24:25], v[156:157], v[66:67]
	v_pk_fma_f32 v[70:71], v[24:25], v[172:173], v[70:71]
	v_pk_fma_f32 v[66:67], v[26:27], v[158:159], v[66:67]
	v_pk_fma_f32 v[70:71], v[26:27], v[174:175], v[70:71]
	v_pk_fma_f32 v[66:67], v[28:29], v[160:161], v[66:67]
	v_pk_fma_f32 v[70:71], v[28:29], v[176:177], v[70:71]
	v_pk_fma_f32 v[66:67], v[30:31], v[162:163], v[66:67]
	v_pk_fma_f32 v[70:71], v[30:31], v[178:179], v[70:71]
	s_waitcnt lgkmcnt(2)
	v_pk_fma_f32 v[64:65], v[32:33], v[192:193], v[64:65]
	v_pk_fma_f32 v[68:69], v[32:33], v[208:209], v[68:69]
	v_pk_fma_f32 v[64:65], v[34:35], v[194:195], v[64:65]
	v_pk_fma_f32 v[68:69], v[34:35], v[210:211], v[68:69]
	v_pk_fma_f32 v[64:65], v[36:37], v[196:197], v[64:65]
	v_pk_fma_f32 v[68:69], v[36:37], v[212:213], v[68:69]
	v_pk_fma_f32 v[64:65], v[38:39], v[198:199], v[64:65]
	v_pk_fma_f32 v[68:69], v[38:39], v[214:215], v[68:69]
	v_pk_fma_f32 v[64:65], v[40:41], v[200:201], v[64:65]
	v_pk_fma_f32 v[68:69], v[40:41], v[216:217], v[68:69]
	v_pk_fma_f32 v[64:65], v[42:43], v[202:203], v[64:65]
	v_pk_fma_f32 v[68:69], v[42:43], v[218:219], v[68:69]
	v_pk_fma_f32 v[64:65], v[44:45], v[204:205], v[64:65]
	v_pk_fma_f32 v[68:69], v[44:45], v[220:221], v[68:69]
	v_pk_fma_f32 v[64:65], v[46:47], v[206:207], v[64:65]
	v_pk_fma_f32 v[68:69], v[46:47], v[222:223], v[68:69]
	v_pk_fma_f32 v[66:67], v[48:49], v[192:193], v[66:67]
	v_pk_fma_f32 v[70:71], v[48:49], v[208:209], v[70:71]
	v_pk_fma_f32 v[66:67], v[50:51], v[194:195], v[66:67]
	v_pk_fma_f32 v[70:71], v[50:51], v[210:211], v[70:71]
	v_pk_fma_f32 v[66:67], v[52:53], v[196:197], v[66:67]
	v_pk_fma_f32 v[70:71], v[52:53], v[212:213], v[70:71]
	v_pk_fma_f32 v[66:67], v[54:55], v[198:199], v[66:67]
	v_pk_fma_f32 v[70:71], v[54:55], v[214:215], v[70:71]
	v_pk_fma_f32 v[66:67], v[56:57], v[200:201], v[66:67]
	v_pk_fma_f32 v[70:71], v[56:57], v[216:217], v[70:71]
	v_pk_fma_f32 v[66:67], v[58:59], v[202:203], v[66:67]
	v_pk_fma_f32 v[70:71], v[58:59], v[218:219], v[70:71]
	v_pk_fma_f32 v[66:67], v[60:61], v[204:205], v[66:67]
	v_pk_fma_f32 v[70:71], v[60:61], v[220:221], v[70:71]
	v_pk_fma_f32 v[66:67], v[62:63], v[206:207], v[66:67]
	v_pk_fma_f32 v[70:71], v[62:63], v[222:223], v[70:71]
	ds_read_b32 v249, v251 offset:0
	ds_read_b32 v250, v251 offset:128
	v_lshlrev_b32_e32 v240, 16, v85
	v_lshlrev_b32_e32 v241, 16, v86
	s_waitcnt lgkmcnt(0)
; template <bool ID> __device__ __forceinline__ void rwkv_scan(const bf16_t* __restrict__ R, const bf16_t* __restrict__ EW, const bf16_t* __restrict__ K, const bf16_t* __restrict__ V, ...
;     ...
;         L[lane] = bf2f(q2[4]); L[64 + lane] = __expf(-bf2f(q1[1])); L[128 + lane] = bf2f(q1[5]); L[192 + lane] = bf2f(q1[2]); L[256 + lane] = bf2f(q1[0]);
;         const float v = bf2f(q1[3]);
; #pragma unroll
;         for (int j = 0; j < 6; ++j) q1[j] = q2[j];
;         { const unsigned o = base + (unsigned)(s + 2 < nsteps ? s + 2 : nsteps - 1) * 512u; q2[0] = R[o]; q2[1] = EW[o]; q2[2] = K[o]; q2[3] = V[o]; q2[4] = A[o]; q2[5] = B[o]; }
;         const f2 sav2 = {sav, sav}, sai2 = {sai, sai}, v2 = {v, v};
;         f2 yv = {0.f, 0.f}, yi = {0.f, 0.f}, yv1 = {0.f, 0.f}, yi1 = {0.f, 0.f}, nv = {0.f, 0.f}, ni = {0.f, 0.f}, nv1 = {0.f, 0.f}, ni1 = {0.f, 0.f};
;         f32x4 ca = pa[0], cw = pa[16], cb = pa[32], ck = pa[48], cr = pa[64];
; #pragma unroll
;         for (int q = 0; q < 16; ++q) {
;             const f32x4 a4 = ca, w4 = cw, b4 = cb, k4 = ck, r4 = cr;
;             if (q < 15) { ca = pa[1 + q]; cw = pa[17 + q]; cb = pa[33 + q]; ck = pa[49 + q]; cr = pa[65 + q]; }
;             __builtin_amdgcn_sched_barrier(0);
;             { const f2 a2 = {a4[0], a4[1]}, w2 = {w4[0], w4[1]}, b2 = {b4[0], b4[1]}, k2 = {k4[0], k4[1]}, r2 = {r4[0], r4[1]};
;               f2 tv = sav2 * b2; tv = pfma(v2, k2, tv); Sv[2 * q] = pfma(Sv[2 * q], w2, tv); yv = pfma(Sv[2 * q], r2, yv); nv = pfma(Sv[2 * q], a2, nv);
;               if (ID) { const f2 ti = sai2 * b2; Si[2 * q] = pfma(Si[2 * q], w2, ti); yi = pfma(Si[2 * q], r2, yi); ni = pfma(Si[2 * q], a2, ni); } }
;             { const f2 a2 = {a4[2], a4[3]}, w2 = {w4[2], w4[3]}, b2 = {b4[2], b4[3]}, k2 = {k4[2], k4[3]}, r2 = {r4[2], r4[3]};
;               f2 tv = sav2 * b2; tv = pfma(v2, k2, tv); Sv[2 * q + 1] = pfma(Sv[2 * q + 1], w2, tv); yv1 = pfma(Sv[2 * q + 1], r2, yv1); nv1 = pfma(Sv[2 * q + 1], a2, nv1);
;               if (ID) { const f2 ti = sai2 * b2; Si[2 * q + 1] = pfma(Si[2 * q + 1], w2, ti); yi1 = pfma(Si[2 * q + 1], r2, yi1); ni1 = pfma(Si[2 * q + 1], a2, ni1); } }
;         }
;         sav = (nv[0] + nv[1]) + (nv1[0] + nv1[1]); sai = (ni[0] + ni[1]) + (ni1[0] + ni1[1]);
;         const unsigned cbo = base + (unsigned)s * 512u;
	v_mul_f32_e32 v240, v240, v249
	v_mul_f32_e32 v241, v241, v250
	v_add_f32_e32 v68, v68, v69
	v_add_f32_e32 v70, v70, v71
	v_add_f32_e32 v64, v64, v65
	v_add_f32_e32 v66, v66, v67
	v_permlane32_swap_b32_e32 v68, v70
	s_nop 0
	v_permlane32_swap_b32_e32 v64, v66
	v_add_f32_e32 v244, v68, v70
	v_add_f32_e32 v64, v64, v66
	v_bfe_u32 v66, v64, 16, 1
	v_add3_u32 v66, v64, v66, s69
	global_store_short_d16_hi v72, v66, s[24:25] offset:-4096
	v_add_u32_e32 v72, 0x400, v72
	v_lshl_add_u64 v[74:75], v[74:75], 0, s[54:55]
	ds_read_b128 v[192:195], v76 offset:256
	ds_read_b128 v[196:199], v76 offset:288
	ds_read_b128 v[200:203], v76 offset:320
	ds_read_b128 v[204:207], v76 offset:352
	ds_read_b128 v[208:211], v76 offset:512
	ds_read_b128 v[212:215], v76 offset:544
	ds_read_b128 v[216:219], v76 offset:576
	ds_read_b128 v[220:223], v76 offset:608
	global_load_ushort v82, v72, s[4:5] offset:0
	global_load_ushort v83, v72, s[0:1] offset:0
	global_load_ushort v84, v72, s[12:13] offset:1024
	global_load_ushort v85, v[74:75], off offset:0
	global_load_ushort v86, v[74:75], off offset:64
	v_mfma_f32_32x32x1_2b_f32 v[0:31], v240, v244, v[0:31]
	ds_read_b128 v[148:151], v76 offset:384
	ds_read_b128 v[152:155], v76 offset:416
	ds_read_b128 v[156:159], v76 offset:448
	ds_read_b128 v[160:163], v76 offset:480
	ds_read_b128 v[164:167], v76 offset:640
	ds_read_b128 v[168:171], v76 offset:672
	ds_read_b128 v[172:175], v76 offset:704
	ds_read_b128 v[176:179], v76 offset:736
	v_mfma_f32_32x32x1_2b_f32 v[32:63], v241, v244, v[32:63]
	s_waitcnt vmcnt(17)
	v_lshlrev_b32_e32 v78, 16, v88
	v_mul_f32_e32 v78, 0xbfb8aa3b, v78
	v_exp_f32_e32 v78, v78
	v_lshlrev_b32_e32 v79, 16, v89
	v_lshlrev_b32_e32 v80, 16, v90
	v_mul_f32_e32 v246, v246, v78
	v_mul_f32_e32 v79, v79, v246
	v_mul_f32_e32 v80, v80, v246
	v_rcp_f32_e32 v248, v246
	s_nop 0
	ds_write2st64_b32 v77, v248, v79 offset0:3 offset1:4
	ds_write_b32 v77, v80 offset:1280
	s_waitcnt lgkmcnt(10)
	v_pk_mul_f32 v[64:65], v[0:1], v[192:193]
	v_pk_mul_f32 v[68:69], v[0:1], v[208:209]
	v_pk_fma_f32 v[64:65], v[2:3], v[194:195], v[64:65]
	v_pk_fma_f32 v[68:69], v[2:3], v[210:211], v[68:69]
	v_pk_fma_f32 v[64:65], v[4:5], v[196:197], v[64:65]
	v_pk_fma_f32 v[68:69], v[4:5], v[212:213], v[68:69]
	v_pk_fma_f32 v[64:65], v[6:7], v[198:199], v[64:65]
	v_pk_fma_f32 v[68:69], v[6:7], v[214:215], v[68:69]
	v_pk_fma_f32 v[64:65], v[8:9], v[200:201], v[64:65]
	v_pk_fma_f32 v[68:69], v[8:9], v[216:217], v[68:69]
	v_pk_fma_f32 v[64:65], v[10:11], v[202:203], v[64:65]
	v_pk_fma_f32 v[68:69], v[10:11], v[218:219], v[68:69]
	v_pk_fma_f32 v[64:65], v[12:13], v[204:205], v[64:65]
	v_pk_fma_f32 v[68:69], v[12:13], v[220:221], v[68:69]
	v_pk_fma_f32 v[64:65], v[14:15], v[206:207], v[64:65]
	v_pk_fma_f32 v[68:69], v[14:15], v[222:223], v[68:69]
	v_pk_mul_f32 v[66:67], v[16:17], v[192:193]
	v_pk_mul_f32 v[70:71], v[16:17], v[208:209]
	v_pk_fma_f32 v[66:67], v[18:19], v[194:195], v[66:67]
	v_pk_fma_f32 v[70:71], v[18:19], v[210:211], v[70:71]
	v_pk_fma_f32 v[66:67], v[20:21], v[196:197], v[66:67]
	v_pk_fma_f32 v[70:71], v[20:21], v[212:213], v[70:71]
	v_pk_fma_f32 v[66:67], v[22:23], v[198:199], v[66:67]
	v_pk_fma_f32 v[70:71], v[22:23], v[214:215], v[70:71]
	v_pk_fma_f32 v[66:67], v[24:25], v[200:201], v[66:67]
	v_pk_fma_f32 v[70:71], v[24:25], v[216:217], v[70:71]
	v_pk_fma_f32 v[66:67], v[26:27], v[202:203], v[66:67]
	v_pk_fma_f32 v[70:71], v[26:27], v[218:219], v[70:71]
	v_pk_fma_f32 v[66:67], v[28:29], v[204:205], v[66:67]
	v_pk_fma_f32 v[70:71], v[28:29], v[220:221], v[70:71]
	v_pk_fma_f32 v[66:67], v[30:31], v[206:207], v[66:67]
	v_pk_fma_f32 v[70:71], v[30:31], v[222:223], v[70:71]
	s_waitcnt lgkmcnt(2)
	v_pk_fma_f32 v[64:65], v[32:33], v[148:149], v[64:65]
	v_pk_fma_f32 v[68:69], v[32:33], v[164:165], v[68:69]
	v_pk_fma_f32 v[64:65], v[34:35], v[150:151], v[64:65]
	v_pk_fma_f32 v[68:69], v[34:35], v[166:167], v[68:69]
	v_pk_fma_f32 v[64:65], v[36:37], v[152:153], v[64:65]
	v_pk_fma_f32 v[68:69], v[36:37], v[168:169], v[68:69]
	v_pk_fma_f32 v[64:65], v[38:39], v[154:155], v[64:65]
	v_pk_fma_f32 v[68:69], v[38:39], v[170:171], v[68:69]
	v_pk_fma_f32 v[64:65], v[40:41], v[156:157], v[64:65]
	v_pk_fma_f32 v[68:69], v[40:41], v[172:173], v[68:69]
	v_pk_fma_f32 v[64:65], v[42:43], v[158:159], v[64:65]
	v_pk_fma_f32 v[68:69], v[42:43], v[174:175], v[68:69]
	v_pk_fma_f32 v[64:65], v[44:45], v[160:161], v[64:65]
	v_pk_fma_f32 v[68:69], v[44:45], v[176:177], v[68:69]
	v_pk_fma_f32 v[64:65], v[46:47], v[162:163], v[64:65]
	v_pk_fma_f32 v[68:69], v[46:47], v[178:179], v[68:69]
	v_pk_fma_f32 v[66:67], v[48:49], v[148:149], v[66:67]
	v_pk_fma_f32 v[70:71], v[48:49], v[164:165], v[70:71]
	v_pk_fma_f32 v[66:67], v[50:51], v[150:151], v[66:67]
	v_pk_fma_f32 v[70:71], v[50:51], v[166:167], v[70:71]
	v_pk_fma_f32 v[66:67], v[52:53], v[152:153], v[66:67]
	v_pk_fma_f32 v[70:71], v[52:53], v[168:169], v[70:71]
	v_pk_fma_f32 v[66:67], v[54:55], v[154:155], v[66:67]
	v_pk_fma_f32 v[70:71], v[54:55], v[170:171], v[70:71]
	v_pk_fma_f32 v[66:67], v[56:57], v[156:157], v[66:67]
	v_pk_fma_f32 v[70:71], v[56:57], v[172:173], v[70:71]
	v_pk_fma_f32 v[66:67], v[58:59], v[158:159], v[66:67]
	v_pk_fma_f32 v[70:71], v[58:59], v[174:175], v[70:71]
	v_pk_fma_f32 v[66:67], v[60:61], v[160:161], v[66:67]
	v_pk_fma_f32 v[70:71], v[60:61], v[176:177], v[70:71]
	v_pk_fma_f32 v[66:67], v[62:63], v[162:163], v[66:67]
	v_pk_fma_f32 v[70:71], v[62:63], v[178:179], v[70:71]
	ds_read_b32 v249, v251 offset:768
	ds_read_b32 v250, v251 offset:896
	v_lshlrev_b32_e32 v240, 16, v91
	v_lshlrev_b32_e32 v241, 16, v92
	s_waitcnt lgkmcnt(0)
	v_mul_f32_e32 v240, v240, v249
	v_mul_f32_e32 v241, v241, v250
	v_add_f32_e32 v68, v68, v69
	v_add_f32_e32 v70, v70, v71
	v_add_f32_e32 v64, v64, v65
	v_add_f32_e32 v66, v66, v67
	v_permlane32_swap_b32_e32 v68, v70
	s_nop 0
	v_permlane32_swap_b32_e32 v64, v66
	v_add_f32_e32 v244, v68, v70
	v_add_f32_e32 v64, v64, v66
	v_bfe_u32 v66, v64, 16, 1
	v_add3_u32 v66, v64, v66, s69
	global_store_short_d16_hi v72, v66, s[24:25] offset:-4096
	v_add_u32_e32 v72, 0x400, v72
	v_lshl_add_u64 v[74:75], v[74:75], 0, s[54:55]
	s_and_b32 s14, s41, 15
	s_cmp_eq_u32 s14, 15
	s_cbranch_scc1 .Lscan_i_s3x
; template <bool ID> __device__ __forceinline__ void rwkv_scan(const bf16_t* __restrict__ R, const bf16_t* __restrict__ EW, const bf16_t* __restrict__ K, const bf16_t* __restrict__ V, ...
;     ...
;         L[lane] = bf2f(q2[4]); L[64 + lane] = __expf(-bf2f(q1[1])); L[128 + lane] = bf2f(q1[5]); L[192 + lane] = bf2f(q1[2]); L[256 + lane] = bf2f(q1[0]);
;         const float v = bf2f(q1[3]);
; #pragma unroll
;         for (int j = 0; j < 6; ++j) q1[j] = q2[j];
;         { const unsigned o = base + (unsigned)(s + 2 < nsteps ? s + 2 : nsteps - 1) * 512u; q2[0] = R[o]; q2[1] = EW[o]; q2[2] = K[o]; q2[3] = V[o]; q2[4] = A[o]; q2[5] = B[o]; }
;         const f2 sav2 = {sav, sav}, sai2 = {sai, sai}, v2 = {v, v};
;         f2 yv = {0.f, 0.f}, yi = {0.f, 0.f}, yv1 = {0.f, 0.f}, yi1 = {0.f, 0.f}, nv = {0.f, 0.f}, ni = {0.f, 0.f}, nv1 = {0.f, 0.f}, ni1 = {0.f, 0.f};
;         f32x4 ca = pa[0], cw = pa[16], cb = pa[32], ck = pa[48], cr = pa[64];
; #pragma unroll
;         for (int q = 0; q < 16; ++q) {
;             const f32x4 a4 = ca, w4 = cw, b4 = cb, k4 = ck, r4 = cr;
;             if (q < 15) { ca = pa[1 + q]; cw = pa[17 + q]; cb = pa[33 + q]; ck = pa[49 + q]; cr = pa[65 + q]; }
;             __builtin_amdgcn_sched_barrier(0);
;             { const f2 a2 = {a4[0], a4[1]}, w2 = {w4[0], w4[1]}, b2 = {b4[0], b4[1]}, k2 = {k4[0], k4[1]}, r2 = {r4[0], r4[1]};
;               f2 tv = sav2 * b2; tv = pfma(v2, k2, tv); Sv[2 * q] = pfma(Sv[2 * q], w2, tv); yv = pfma(Sv[2 * q], r2, yv); nv = pfma(Sv[2 * q], a2, nv);
;               if (ID) { const f2 ti = sai2 * b2; Si[2 * q] = pfma(Si[2 * q], w2, ti); yi = pfma(Si[2 * q], r2, yi); ni = pfma(Si[2 * q], a2, ni); } }
;             { const f2 a2 = {a4[2], a4[3]}, w2 = {w4[2], w4[3]}, b2 = {b4[2], b4[3]}, k2 = {k4[2], k4[3]}, r2 = {r4[2], r4[3]};
;               f2 tv = sav2 * b2; tv = pfma(v2, k2, tv); Sv[2 * q + 1] = pfma(Sv[2 * q + 1], w2, tv); yv1 = pfma(Sv[2 * q + 1], r2, yv1); nv1 = pfma(Sv[2 * q + 1], a2, nv1);
;               if (ID) { const f2 ti = sai2 * b2; Si[2 * q + 1] = pfma(Si[2 * q + 1], w2, ti); yi1 = pfma(Si[2 * q + 1], r2, yi1); ni1 = pfma(Si[2 * q + 1], a2, ni1); } }
;         }
;         sav = (nv[0] + nv[1]) + (nv1[0] + nv1[1]); sai = (ni[0] + ni[1]) + (ni1[0] + ni1[1]);
;         const unsigned cbo = base + (unsigned)s * 512u;
	ds_read_b128 v[148:151], v76 offset:1024
	ds_read_b128 v[152:155], v76 offset:1056
	ds_read_b128 v[156:159], v76 offset:1088
	ds_read_b128 v[160:163], v76 offset:1120
	ds_read_b128 v[164:167], v76 offset:1280
	ds_read_b128 v[168:171], v76 offset:1312
	ds_read_b128 v[172:175], v76 offset:1344
	ds_read_b128 v[176:179], v76 offset:1376
	global_load_ushort v88, v72, s[4:5] offset:0
	global_load_ushort v89, v72, s[0:1] offset:0
	global_load_ushort v90, v72, s[12:13] offset:1024
	global_load_ushort v91, v[74:75], off offset:0
	global_load_ushort v92, v[74:75], off offset:64
	v_mfma_f32_32x32x1_2b_f32 v[0:31], v240, v244, v[0:31]
	ds_read_b128 v[192:195], v76 offset:1152
	ds_read_b128 v[196:199], v76 offset:1184
	ds_read_b128 v[200:203], v76 offset:1216
	ds_read_b128 v[204:207], v76 offset:1248
	ds_read_b128 v[208:211], v76 offset:1408
	ds_read_b128 v[212:215], v76 offset:1440
	ds_read_b128 v[216:219], v76 offset:1472
	ds_read_b128 v[220:223], v76 offset:1504
	v_mfma_f32_32x32x1_2b_f32 v[32:63], v241, v244, v[32:63]
	s_waitcnt vmcnt(18)
	v_lshlrev_b32_e32 v78, 16, v224
	v_mul_f32_e32 v78, 0xbfb8aa3b, v78
	v_exp_f32_e32 v78, v78
	v_lshlrev_b32_e32 v79, 16, v225
	v_lshlrev_b32_e32 v80, 16, v226
	v_mul_f32_e32 v246, v246, v78
	v_mul_f32_e32 v79, v79, v246
	v_mul_f32_e32 v80, v80, v246
	v_rcp_f32_e32 v248, v246
	s_nop 0
	ds_write2st64_b32 v77, v248, v79 offset0:0 offset1:1
	ds_write_b32 v77, v80 offset:512
	s_waitcnt lgkmcnt(10)
	v_pk_mul_f32 v[64:65], v[0:1], v[148:149]
	v_pk_mul_f32 v[68:69], v[0:1], v[164:165]
	v_pk_fma_f32 v[64:65], v[2:3], v[150:151], v[64:65]
	v_pk_fma_f32 v[68:69], v[2:3], v[166:167], v[68:69]
	v_pk_fma_f32 v[64:65], v[4:5], v[152:153], v[64:65]
	v_pk_fma_f32 v[68:69], v[4:5], v[168:169], v[68:69]
	v_pk_fma_f32 v[64:65], v[6:7], v[154:155], v[64:65]
	v_pk_fma_f32 v[68:69], v[6:7], v[170:171], v[68:69]
	v_pk_fma_f32 v[64:65], v[8:9], v[156:157], v[64:65]
	v_pk_fma_f32 v[68:69], v[8:9], v[172:173], v[68:69]
	v_pk_fma_f32 v[64:65], v[10:11], v[158:159], v[64:65]
	v_pk_fma_f32 v[68:69], v[10:11], v[174:175], v[68:69]
	v_pk_fma_f32 v[64:65], v[12:13], v[160:161], v[64:65]
	v_pk_fma_f32 v[68:69], v[12:13], v[176:177], v[68:69]
	v_pk_fma_f32 v[64:65], v[14:15], v[162:163], v[64:65]
	v_pk_fma_f32 v[68:69], v[14:15], v[178:179], v[68:69]
	v_pk_mul_f32 v[66:67], v[16:17], v[148:149]
	v_pk_mul_f32 v[70:71], v[16:17], v[164:165]
	v_pk_fma_f32 v[66:67], v[18:19], v[150:151], v[66:67]
	v_pk_fma_f32 v[70:71], v[18:19], v[166:167], v[70:71]
	v_pk_fma_f32 v[66:67], v[20:21], v[152:153], v[66:67]
	v_pk_fma_f32 v[70:71], v[20:21], v[168:169], v[70:71]
	v_pk_fma_f32 v[66:67], v[22:23], v[154:155], v[66:67]
	v_pk_fma_f32 v[70:71], v[22:23], v[170:171], v[70:71]
	v_pk_fma_f32 v[66:67], v[24:25], v[156:157], v[66:67]
	v_pk_fma_f32 v[70:71], v[24:25], v[172:173], v[70:71]
	v_pk_fma_f32 v[66:67], v[26:27], v[158:159], v[66:67]
	v_pk_fma_f32 v[70:71], v[26:27], v[174:175], v[70:71]
	v_pk_fma_f32 v[66:67], v[28:29], v[160:161], v[66:67]
	v_pk_fma_f32 v[70:71], v[28:29], v[176:177], v[70:71]
	v_pk_fma_f32 v[66:67], v[30:31], v[162:163], v[66:67]
	v_pk_fma_f32 v[70:71], v[30:31], v[178:179], v[70:71]
	s_waitcnt lgkmcnt(2)
	v_pk_fma_f32 v[64:65], v[32:33], v[192:193], v[64:65]
	v_pk_fma_f32 v[68:69], v[32:33], v[208:209], v[68:69]
	v_pk_fma_f32 v[64:65], v[34:35], v[194:195], v[64:65]
	v_pk_fma_f32 v[68:69], v[34:35], v[210:211], v[68:69]
	v_pk_fma_f32 v[64:65], v[36:37], v[196:197], v[64:65]
	v_pk_fma_f32 v[68:69], v[36:37], v[212:213], v[68:69]
	v_pk_fma_f32 v[64:65], v[38:39], v[198:199], v[64:65]
	v_pk_fma_f32 v[68:69], v[38:39], v[214:215], v[68:69]
	v_pk_fma_f32 v[64:65], v[40:41], v[200:201], v[64:65]
	v_pk_fma_f32 v[68:69], v[40:41], v[216:217], v[68:69]
	v_pk_fma_f32 v[64:65], v[42:43], v[202:203], v[64:65]
	v_pk_fma_f32 v[68:69], v[42:43], v[218:219], v[68:69]
	v_pk_fma_f32 v[64:65], v[44:45], v[204:205], v[64:65]
	v_pk_fma_f32 v[68:69], v[44:45], v[220:221], v[68:69]
	v_pk_fma_f32 v[64:65], v[46:47], v[206:207], v[64:65]
	v_pk_fma_f32 v[68:69], v[46:47], v[222:223], v[68:69]
	v_pk_fma_f32 v[66:67], v[48:49], v[192:193], v[66:67]
	v_pk_fma_f32 v[70:71], v[48:49], v[208:209], v[70:71]
	v_pk_fma_f32 v[66:67], v[50:51], v[194:195], v[66:67]
	v_pk_fma_f32 v[70:71], v[50:51], v[210:211], v[70:71]
	v_pk_fma_f32 v[66:67], v[52:53], v[196:197], v[66:67]
	v_pk_fma_f32 v[70:71], v[52:53], v[212:213], v[70:71]
	v_pk_fma_f32 v[66:67], v[54:55], v[198:199], v[66:67]
	v_pk_fma_f32 v[70:71], v[54:55], v[214:215], v[70:71]
	v_pk_fma_f32 v[66:67], v[56:57], v[200:201], v[66:67]
	v_pk_fma_f32 v[70:71], v[56:57], v[216:217], v[70:71]
	v_pk_fma_f32 v[66:67], v[58:59], v[202:203], v[66:67]
	v_pk_fma_f32 v[70:71], v[58:59], v[218:219], v[70:71]
	v_pk_fma_f32 v[66:67], v[60:61], v[204:205], v[66:67]
	v_pk_fma_f32 v[70:71], v[60:61], v[220:221], v[70:71]
	v_pk_fma_f32 v[66:67], v[62:63], v[206:207], v[66:67]
	v_pk_fma_f32 v[70:71], v[62:63], v[222:223], v[70:71]
	ds_read_b32 v249, v251 offset:0
	ds_read_b32 v250, v251 offset:128
	v_lshlrev_b32_e32 v240, 16, v227
	v_lshlrev_b32_e32 v241, 16, v228
	s_waitcnt lgkmcnt(0)
	v_mul_f32_e32 v240, v240, v249
	v_mul_f32_e32 v241, v241, v250
	v_add_f32_e32 v68, v68, v69
	v_add_f32_e32 v70, v70, v71
	v_add_f32_e32 v64, v64, v65
	v_add_f32_e32 v66, v66, v67
	v_permlane32_swap_b32_e32 v68, v70
	s_nop 0
	v_permlane32_swap_b32_e32 v64, v66
	v_add_f32_e32 v244, v68, v70
	v_add_f32_e32 v64, v64, v66
	v_bfe_u32 v66, v64, 16, 1
	v_add3_u32 v66, v64, v66, s69
	global_store_short_d16_hi v72, v66, s[24:25] offset:-4096
	v_add_u32_e32 v72, 0x400, v72
	v_lshl_add_u64 v[74:75], v[74:75], 0, s[54:55]
	s_branch .Lscan_i_s3e
; template <bool ID> __device__ __forceinline__ void rwkv_scan(const bf16_t* __restrict__ R, const bf16_t* __restrict__ EW, const bf16_t* __restrict__ K, const bf16_t* __restrict__ V, ...
;     ...
;         L[lane] = bf2f(q2[4]); L[64 + lane] = __expf(-bf2f(q1[1])); L[128 + lane] = bf2f(q1[5]); L[192 + lane] = bf2f(q1[2]); L[256 + lane] = bf2f(q1[0]);
;         const float v = bf2f(q1[3]);
; #pragma unroll
;         for (int j = 0; j < 6; ++j) q1[j] = q2[j];
;         { const unsigned o = base + (unsigned)(s + 2 < nsteps ? s + 2 : nsteps - 1) * 512u; q2[0] = R[o]; q2[1] = EW[o]; q2[2] = K[o]; q2[3] = V[o]; q2[4] = A[o]; q2[5] = B[o]; }
;         const f2 sav2 = {sav, sav}, sai2 = {sai, sai}, v2 = {v, v};
;         f2 yv = {0.f, 0.f}, yi = {0.f, 0.f}, yv1 = {0.f, 0.f}, yi1 = {0.f, 0.f}, nv = {0.f, 0.f}, ni = {0.f, 0.f}, nv1 = {0.f, 0.f}, ni1 = {0.f, 0.f};
;         f32x4 ca = pa[0], cw = pa[16], cb = pa[32], ck = pa[48], cr = pa[64];
; #pragma unroll
;         for (int q = 0; q < 16; ++q) {
;             const f32x4 a4 = ca, w4 = cw, b4 = cb, k4 = ck, r4 = cr;
;             if (q < 15) { ca = pa[1 + q]; cw = pa[17 + q]; cb = pa[33 + q]; ck = pa[49 + q]; cr = pa[65 + q]; }
;             __builtin_amdgcn_sched_barrier(0);
;             { const f2 a2 = {a4[0], a4[1]}, w2 = {w4[0], w4[1]}, b2 = {b4[0], b4[1]}, k2 = {k4[0], k4[1]}, r2 = {r4[0], r4[1]};
;               f2 tv = sav2 * b2; tv = pfma(v2, k2, tv); Sv[2 * q] = pfma(Sv[2 * q], w2, tv); yv = pfma(Sv[2 * q], r2, yv); nv = pfma(Sv[2 * q], a2, nv);
;               if (ID) { const f2 ti = sai2 * b2; Si[2 * q] = pfma(Si[2 * q], w2, ti); yi = pfma(Si[2 * q], r2, yi); ni = pfma(Si[2 * q], a2, ni); } }
;             { const f2 a2 = {a4[2], a4[3]}, w2 = {w4[2], w4[3]}, b2 = {b4[2], b4[3]}, k2 = {k4[2], k4[3]}, r2 = {r4[2], r4[3]};
;               f2 tv = sav2 * b2; tv = pfma(v2, k2, tv); Sv[2 * q + 1] = pfma(Sv[2 * q + 1], w2, tv); yv1 = pfma(Sv[2 * q + 1], r2, yv1); nv1 = pfma(Sv[2 * q + 1], a2, nv1);
;               if (ID) { const f2 ti = sai2 * b2; Si[2 * q + 1] = pfma(Si[2 * q + 1], w2, ti); yi1 = pfma(Si[2 * q + 1], r2, yi1); ni1 = pfma(Si[2 * q + 1], a2, ni1); } }
;         }
;         sav = (nv[0] + nv[1]) + (nv1[0] + nv1[1]); sai = (ni[0] + ni[1]) + (ni1[0] + ni1[1]);
;         const unsigned cbo = base + (unsigned)s * 512u;
.Lscan_i_s3x:
	ds_read_b128 v[148:151], v76 offset:1024
	ds_read_b128 v[152:155], v76 offset:1056
	ds_read_b128 v[156:159], v76 offset:1088
	ds_read_b128 v[160:163], v76 offset:1120
	ds_read_b128 v[164:167], v76 offset:1280
	ds_read_b128 v[168:171], v76 offset:1312
	ds_read_b128 v[172:175], v76 offset:1344
	ds_read_b128 v[176:179], v76 offset:1376
	global_load_ushort v88, v72, s[4:5] offset:0
	global_load_ushort v89, v72, s[0:1] offset:0
	global_load_ushort v90, v72, s[12:13] offset:1024
	global_load_ushort v91, v[74:75], off offset:0
	global_load_ushort v92, v[74:75], off offset:64
	v_mfma_f32_32x32x1_2b_f32 v[0:31], v240, v244, v[0:31]
	ds_read_b128 v[192:195], v76 offset:1152
	ds_read_b128 v[196:199], v76 offset:1184
	ds_read_b128 v[200:203], v76 offset:1216
	ds_read_b128 v[204:207], v76 offset:1248
	ds_read_b128 v[208:211], v76 offset:1408
	ds_read_b128 v[212:215], v76 offset:1440
	ds_read_b128 v[216:219], v76 offset:1472
	ds_read_b128 v[220:223], v76 offset:1504
	v_mfma_f32_32x32x1_2b_f32 v[32:63], v241, v244, v[32:63]
	s_waitcnt vmcnt(18)
	s_waitcnt lgkmcnt(8)
	s_nop 6
	v_pk_mul_f32 v[64:65], v[0:1], v[148:149]
	v_pk_mul_f32 v[68:69], v[0:1], v[164:165]
	v_pk_fma_f32 v[64:65], v[2:3], v[150:151], v[64:65]
	v_pk_fma_f32 v[68:69], v[2:3], v[166:167], v[68:69]
	v_pk_fma_f32 v[64:65], v[4:5], v[152:153], v[64:65]
	v_pk_fma_f32 v[68:69], v[4:5], v[168:169], v[68:69]
	v_pk_fma_f32 v[64:65], v[6:7], v[154:155], v[64:65]
	v_pk_fma_f32 v[68:69], v[6:7], v[170:171], v[68:69]
	v_pk_fma_f32 v[64:65], v[8:9], v[156:157], v[64:65]
	v_pk_fma_f32 v[68:69], v[8:9], v[172:173], v[68:69]
	v_pk_fma_f32 v[64:65], v[10:11], v[158:159], v[64:65]
	v_pk_fma_f32 v[68:69], v[10:11], v[174:175], v[68:69]
	v_pk_fma_f32 v[64:65], v[12:13], v[160:161], v[64:65]
	v_pk_fma_f32 v[68:69], v[12:13], v[176:177], v[68:69]
	v_pk_fma_f32 v[64:65], v[14:15], v[162:163], v[64:65]
	v_pk_fma_f32 v[68:69], v[14:15], v[178:179], v[68:69]
	v_pk_mul_f32 v[66:67], v[16:17], v[148:149]
	v_pk_mul_f32 v[70:71], v[16:17], v[164:165]
	v_pk_fma_f32 v[66:67], v[18:19], v[150:151], v[66:67]
	v_pk_fma_f32 v[70:71], v[18:19], v[166:167], v[70:71]
	v_pk_fma_f32 v[66:67], v[20:21], v[152:153], v[66:67]
	v_pk_fma_f32 v[70:71], v[20:21], v[168:169], v[70:71]
	v_pk_fma_f32 v[66:67], v[22:23], v[154:155], v[66:67]
	v_pk_fma_f32 v[70:71], v[22:23], v[170:171], v[70:71]
	v_pk_fma_f32 v[66:67], v[24:25], v[156:157], v[66:67]
	v_pk_fma_f32 v[70:71], v[24:25], v[172:173], v[70:71]
	v_pk_fma_f32 v[66:67], v[26:27], v[158:159], v[66:67]
	v_pk_fma_f32 v[70:71], v[26:27], v[174:175], v[70:71]
	v_pk_fma_f32 v[66:67], v[28:29], v[160:161], v[66:67]
	v_pk_fma_f32 v[70:71], v[28:29], v[176:177], v[70:71]
	v_pk_fma_f32 v[66:67], v[30:31], v[162:163], v[66:67]
	v_pk_fma_f32 v[70:71], v[30:31], v[178:179], v[70:71]
	s_waitcnt lgkmcnt(0)
	v_pk_fma_f32 v[64:65], v[32:33], v[192:193], v[64:65]
	v_pk_fma_f32 v[68:69], v[32:33], v[208:209], v[68:69]
	v_pk_fma_f32 v[64:65], v[34:35], v[194:195], v[64:65]
	v_pk_fma_f32 v[68:69], v[34:35], v[210:211], v[68:69]
	v_pk_fma_f32 v[64:65], v[36:37], v[196:197], v[64:65]
	v_pk_fma_f32 v[68:69], v[36:37], v[212:213], v[68:69]
	v_pk_fma_f32 v[64:65], v[38:39], v[198:199], v[64:65]
	v_pk_fma_f32 v[68:69], v[38:39], v[214:215], v[68:69]
	v_pk_fma_f32 v[64:65], v[40:41], v[200:201], v[64:65]
	v_pk_fma_f32 v[68:69], v[40:41], v[216:217], v[68:69]
	v_pk_fma_f32 v[64:65], v[42:43], v[202:203], v[64:65]
	v_pk_fma_f32 v[68:69], v[42:43], v[218:219], v[68:69]
	v_pk_fma_f32 v[64:65], v[44:45], v[204:205], v[64:65]
	v_pk_fma_f32 v[68:69], v[44:45], v[220:221], v[68:69]
	v_pk_fma_f32 v[64:65], v[46:47], v[206:207], v[64:65]
	v_pk_fma_f32 v[68:69], v[46:47], v[222:223], v[68:69]
	v_pk_fma_f32 v[66:67], v[48:49], v[192:193], v[66:67]
	v_pk_fma_f32 v[70:71], v[48:49], v[208:209], v[70:71]
	v_pk_fma_f32 v[66:67], v[50:51], v[194:195], v[66:67]
	v_pk_fma_f32 v[70:71], v[50:51], v[210:211], v[70:71]
	v_pk_fma_f32 v[66:67], v[52:53], v[196:197], v[66:67]
	v_pk_fma_f32 v[70:71], v[52:53], v[212:213], v[70:71]
	v_pk_fma_f32 v[66:67], v[54:55], v[198:199], v[66:67]
	v_pk_fma_f32 v[70:71], v[54:55], v[214:215], v[70:71]
	v_pk_fma_f32 v[66:67], v[56:57], v[200:201], v[66:67]
	v_pk_fma_f32 v[70:71], v[56:57], v[216:217], v[70:71]
	v_pk_fma_f32 v[66:67], v[58:59], v[202:203], v[66:67]
	v_pk_fma_f32 v[70:71], v[58:59], v[218:219], v[70:71]
	v_pk_fma_f32 v[66:67], v[60:61], v[204:205], v[66:67]
	v_pk_fma_f32 v[70:71], v[60:61], v[220:221], v[70:71]
	v_pk_fma_f32 v[66:67], v[62:63], v[206:207], v[66:67]
	v_pk_fma_f32 v[70:71], v[62:63], v[222:223], v[70:71]
	v_add_f32_e32 v68, v68, v69
	v_add_f32_e32 v70, v70, v71
	v_add_f32_e32 v64, v64, v65
	v_add_f32_e32 v66, v66, v67
	v_permlane32_swap_b32_e32 v68, v70
	s_nop 0
	v_permlane32_swap_b32_e32 v64, v66
	v_add_f32_e32 v244, v68, v70
	v_add_f32_e32 v64, v64, v66
	v_bfe_u32 v66, v64, 16, 1
	v_add3_u32 v66, v64, v66, s69
	global_store_short_d16_hi v72, v66, s[24:25] offset:-4096
	ds_write_b32 v77, v246 offset:0
	ds_read_b128 v[148:151], v76 offset:0
	ds_read_b128 v[152:155], v76 offset:32
	ds_read_b128 v[156:159], v76 offset:64
	ds_read_b128 v[160:163], v76 offset:96
	ds_read_b128 v[164:167], v76 offset:128
	ds_read_b128 v[168:171], v76 offset:160
	ds_read_b128 v[172:175], v76 offset:192
	ds_read_b128 v[176:179], v76 offset:224
	s_waitcnt lgkmcnt(0)
; __device__ __forceinline__ f2 pfma(f2 a, f2 b, f2 c) { return __builtin_elementwise_fma(a, b, c); }
; template <bool ID> __device__ __forceinline__ void rwkv_scan(const bf16_t* __restrict__ R, const bf16_t* __restrict__ EW, const bf16_t* __restrict__ K, const bf16_t* __restrict__ V, ...
;     ...
;               f2 tv = sav2 * b2; tv = pfma(v2, k2, tv); Sv[2 * q] = pfma(Sv[2 * q], w2, tv); yv = pfma(Sv[2 * q], r2, yv); nv = pfma(Sv[2 * q], a2, nv);
;               if (ID) { const f2 ti = sai2 * b2; Si[2 * q] = pfma(Si[2 * q], w2, ti); yi = pfma(Si[2 * q], r2, yi); ni = pfma(Si[2 * q], a2, ni); } }
; __device__ void phase_rwkv_scan(const Ctx& p, int l, LAS unsigned char* lds) {
;     ...
;             float* pp = P + (size_t)item2 * 4096 + ln * 64; float* up = UC + (size_t)item2 * 4096 + ln * 64;
; #pragma unroll
;             for (int i = 0; i < 32; i += 2) { *(float4*)(pp + 2 * i) = make_float4(Si[i][0], Si[i][1], Si[i + 1][0], Si[i + 1][1]); *(float4*)(up + 2 * i) = make_float4(Sv[i][0], Sv[i][1], Sv[i + 1][0], Sv[i + 1][1]); }
	v_pk_mul_f32 v[0:1], v[0:1], v[148:149]
	v_pk_mul_f32 v[2:3], v[2:3], v[150:151]
	v_pk_mul_f32 v[4:5], v[4:5], v[152:153]
	v_pk_mul_f32 v[6:7], v[6:7], v[154:155]
	v_pk_mul_f32 v[8:9], v[8:9], v[156:157]
	v_pk_mul_f32 v[10:11], v[10:11], v[158:159]
	v_pk_mul_f32 v[12:13], v[12:13], v[160:161]
	v_pk_mul_f32 v[14:15], v[14:15], v[162:163]
	v_pk_mul_f32 v[32:33], v[32:33], v[164:165]
	v_pk_mul_f32 v[34:35], v[34:35], v[166:167]
	v_pk_mul_f32 v[36:37], v[36:37], v[168:169]
	v_pk_mul_f32 v[38:39], v[38:39], v[170:171]
	v_pk_mul_f32 v[40:41], v[40:41], v[172:173]
	v_pk_mul_f32 v[42:43], v[42:43], v[174:175]
	v_pk_mul_f32 v[44:45], v[44:45], v[176:177]
	v_pk_mul_f32 v[46:47], v[46:47], v[178:179]
	v_pk_mul_f32 v[16:17], v[16:17], v[148:149]
	v_pk_mul_f32 v[18:19], v[18:19], v[150:151]
	v_pk_mul_f32 v[20:21], v[20:21], v[152:153]
	v_pk_mul_f32 v[22:23], v[22:23], v[154:155]
	v_pk_mul_f32 v[24:25], v[24:25], v[156:157]
	v_pk_mul_f32 v[26:27], v[26:27], v[158:159]
	v_pk_mul_f32 v[28:29], v[28:29], v[160:161]
	v_pk_mul_f32 v[30:31], v[30:31], v[162:163]
	v_pk_mul_f32 v[48:49], v[48:49], v[164:165]
	v_pk_mul_f32 v[50:51], v[50:51], v[166:167]
	v_pk_mul_f32 v[52:53], v[52:53], v[168:169]
	v_pk_mul_f32 v[54:55], v[54:55], v[170:171]
	v_pk_mul_f32 v[56:57], v[56:57], v[172:173]
	v_pk_mul_f32 v[58:59], v[58:59], v[174:175]
	v_pk_mul_f32 v[60:61], v[60:61], v[176:177]
	v_pk_mul_f32 v[62:63], v[62:63], v[178:179]
	v_mov_b32_e32 v246, 1.0
	v_lshlrev_b32_e32 v78, 16, v224
	v_mul_f32_e32 v78, 0xbfb8aa3b, v78
	v_exp_f32_e32 v78, v78
	v_lshlrev_b32_e32 v79, 16, v225
	v_lshlrev_b32_e32 v80, 16, v226
	v_mul_f32_e32 v246, v246, v78
	v_mul_f32_e32 v79, v79, v246
	v_mul_f32_e32 v80, v80, v246
	v_rcp_f32_e32 v248, v246
	s_nop 0
	ds_write2st64_b32 v77, v248, v79 offset0:0 offset1:1
	ds_write_b32 v77, v80 offset:512
	ds_read_b32 v249, v251 offset:0
	ds_read_b32 v250, v251 offset:128
	v_lshlrev_b32_e32 v240, 16, v227
	v_lshlrev_b32_e32 v241, 16, v228
	s_waitcnt lgkmcnt(0)
	v_mul_f32_e32 v240, v240, v249
	v_mul_f32_e32 v241, v241, v250
	s_waitcnt lgkmcnt(0)
	v_add_u32_e32 v72, 0x400, v72
	v_lshl_add_u64 v[74:75], v[74:75], 0, s[54:55]
.Lscan_i_s3e:
	s_add_i32 s41, s41, 1
	s_cmpk_lg_i32 s41, 32
	s_cbranch_scc1 .Lscan_i_loop
	s_waitcnt vmcnt(0) lgkmcnt(0)
	s_ashr_i32 s15, s36, 31
	s_mov_b32 s14, s36
	s_lshl_b64 s[14:15], s[14:15], 14
	s_add_u32 s14, s37, s14
	s_addc_u32 s15, s38, s15
	v_and_b32_e32 v79, 31, v139
	v_lshrrev_b32_e32 v78, 5, v139
	v_lshlrev_b32_e32 v79, 8, v79
	v_lshl_add_u32 v79, v78, 4, v79
	v_add_u32_e32 v80, 0x2000, v79
	global_store_dwordx4 v79, v[0:3], s[14:15] offset:0
	global_store_dwordx4 v79, v[4:7], s[14:15] offset:32
	global_store_dwordx4 v79, v[8:11], s[14:15] offset:64
	global_store_dwordx4 v79, v[12:15], s[14:15] offset:96
	global_store_dwordx4 v79, v[32:35], s[14:15] offset:128
	global_store_dwordx4 v79, v[36:39], s[14:15] offset:160
	global_store_dwordx4 v79, v[40:43], s[14:15] offset:192
	global_store_dwordx4 v79, v[44:47], s[14:15] offset:224
	global_store_dwordx4 v80, v[16:19], s[14:15] offset:0
	global_store_dwordx4 v80, v[20:23], s[14:15] offset:32
	global_store_dwordx4 v80, v[24:27], s[14:15] offset:64
	global_store_dwordx4 v80, v[28:31], s[14:15] offset:96
	global_store_dwordx4 v80, v[48:51], s[14:15] offset:128
	global_store_dwordx4 v80, v[52:55], s[14:15] offset:160
	global_store_dwordx4 v80, v[56:59], s[14:15] offset:192
	global_store_dwordx4 v80, v[60:63], s[14:15] offset:224
	s_branch .Lscan_tail
